# xcd barrier: early L1 invalidate + last XCC releases all XGEN words directly (no TOPGEN relay), static generation per site
# speedup vs baseline: 1.0183x; 1.0183x over previous
.LBB0_241:
	v_readlane_b32 s2, v254, 8
	v_readlane_b32 s6, v254, 6
	v_readlane_b32 s7, v254, 7
	v_readlane_b32 s4, v254, 4
	v_readlane_b32 s5, v254, 5
	s_lshl_b32 s2, s2, 8
	s_add_u32 s2, s6, s2
	s_addc_u32 s3, s7, 0
	s_add_u32 s8, s2, 0x2400
	s_addc_u32 s9, s3, 0
	s_add_u32 s2, s2, 0x1400
	s_addc_u32 s3, s3, 0
	s_add_u32 s14, s4, 0x4200
	s_addc_u32 s15, s5, 0
	s_add_u32 s16, s4, 0x7400
	s_addc_u32 s17, s5, 0
	s_add_u32 s18, s6, 0x2400
	s_addc_u32 s19, s7, 0
	v_mov_b32_e32 v4, 1
	v_mov_b32_e32 v5, 0
	global_atomic_add v3, v5, v4, s[2:3] sc0
	s_waitcnt vmcnt(0) lgkmcnt(0)
	buffer_inv sc1
	v_readfirstlane_b32 s10, v2
	v_readfirstlane_b32 s11, v0
	v_readfirstlane_b32 s12, v3
	s_add_i32 s12, s12, 1
	s_cmp_lg_u32 s12, s10
	s_cbranch_scc1 .Lxb1_poll
	buffer_wbl2 sc1
	s_waitcnt vmcnt(0)
	global_atomic_add v3, v5, v4, s[16:17] sc0
	s_waitcnt vmcnt(0)
	v_readfirstlane_b32 s12, v3
	s_add_i32 s12, s12, 1
	s_cmp_lg_u32 s12, s11
	s_cbranch_scc1 .Lxb1_poll
	global_atomic_add v5, v4, s[18:19]
	global_atomic_add v5, v4, s[18:19] offset:256
	global_atomic_add v5, v4, s[18:19] offset:512
	global_atomic_add v5, v4, s[18:19] offset:768
	global_atomic_add v5, v4, s[18:19] offset:1024
	global_atomic_add v5, v4, s[18:19] offset:1280
	global_atomic_add v5, v4, s[18:19] offset:1536
	global_atomic_add v5, v4, s[18:19] offset:1792
	global_atomic_add v5, v4, s[18:19] offset:2048
	global_atomic_add v5, v4, s[18:19] offset:2304
	global_atomic_add v5, v4, s[18:19] offset:2560
	global_atomic_add v5, v4, s[18:19] offset:2816
	global_atomic_add v5, v4, s[18:19] offset:3072
	global_atomic_add v5, v4, s[18:19] offset:3328
	global_atomic_add v5, v4, s[18:19] offset:3584
	global_atomic_add v5, v4, s[18:19] offset:3840
	s_branch .Lxb1_out
.Lxb1_poll:
	s_mov_b32 s22, 0
.Lxb1_spin:
	global_load_dword v1, v5, s[8:9] sc1
	s_add_i32 s22, s22, 1
	s_waitcnt vmcnt(0)
	v_cmp_ne_u32_e32 vcc, 0, v1
	s_cbranch_vccnz .Lxb1_out
	s_sleep 1
	s_and_b32 s12, s22, 0xff
	s_cmp_lg_u32 s12, 0
	s_cbranch_scc1 .Lxb1_spin
	global_load_dword v1, v5, s[14:15] sc1
	s_waitcnt vmcnt(0)
	v_cmp_ne_u32_e32 vcc, 0, v1
	s_cbranch_vccnz .Lxb1_out
	s_cmp_lt_u32 s22, 0x40001
	s_cbranch_scc1 .Lxb1_spin
	global_atomic_add v5, v4, s[14:15]
	s_waitcnt vmcnt(0)
.Lxb1_out:
.LBB0_277:
	s_or_b64 exec, exec, s[0:1]
	v_readlane_b32 s4, v254, 0
	v_readlane_b32 s5, v254, 1
	s_waitcnt lgkmcnt(0)
	s_barrier
	v_mbcnt_lo_u32_b32 v0, -1, 0
	v_mbcnt_hi_u32_b32 v0, -1, v0
	v_readlane_b32 s0, v254, 3
	s_cmpk_gt_i32 s88, 0x4bf
	s_nop 0
	v_add_u32_e32 v0, s0, v0
	s_nop 0
	v_readfirstlane_b32 s16, v0
	s_cbranch_scc0 .LBB0_281
	s_mov_b64 s[0:1], 0
	s_cmpk_gt_u32 s88, 0x4ff
	s_mov_b64 s[2:3], 0
	s_cbranch_scc1 .LBB0_282
	s_cmpk_gt_u32 s88, 0x4ea
	s_cbranch_scc0 .LBB0_704
	s_add_i32 s6, s88, 0xfffffb15
	s_andn2_b64 vcc, exec, s[2:3]
	s_mov_b32 s8, 64
	s_cbranch_vccz .LBB0_705
	s_branch .LBB0_706

.LBB0_692:
	v_readlane_b32 s2, v254, 8
	v_readlane_b32 s6, v254, 6
	v_readlane_b32 s7, v254, 7
	v_readlane_b32 s4, v254, 4
	v_readlane_b32 s5, v254, 5
	s_lshl_b32 s2, s2, 8
	s_add_u32 s2, s6, s2
	s_addc_u32 s3, s7, 0
	s_add_u32 s8, s2, 0x2400
	s_addc_u32 s9, s3, 0
	s_add_u32 s2, s2, 0x1400
	s_addc_u32 s3, s3, 0
	s_add_u32 s14, s4, 0x4200
	s_addc_u32 s15, s5, 0
	s_add_u32 s16, s4, 0x7400
	s_addc_u32 s17, s5, 0
	s_add_u32 s18, s6, 0x2400
	s_addc_u32 s19, s7, 0
	v_mov_b32_e32 v4, 1
	v_mov_b32_e32 v5, 0
	global_atomic_add v3, v5, v4, s[2:3] sc0
	s_waitcnt vmcnt(0) lgkmcnt(0)
	buffer_inv sc1
	v_readfirstlane_b32 s10, v2
	v_readfirstlane_b32 s11, v0
	v_readfirstlane_b32 s12, v3
	s_mul_i32 s10, s10, 2
	s_mul_i32 s11, s11, 2
	s_add_i32 s12, s12, 1
	s_cmp_lg_u32 s12, s10
	s_cbranch_scc1 .Lxb2_poll
	buffer_wbl2 sc1
	s_waitcnt vmcnt(0)
	global_atomic_add v3, v5, v4, s[16:17] sc0
	s_waitcnt vmcnt(0)
	v_readfirstlane_b32 s12, v3
	s_add_i32 s12, s12, 1
	s_cmp_lg_u32 s12, s11
	s_cbranch_scc1 .Lxb2_poll
	global_atomic_add v5, v4, s[18:19]
	global_atomic_add v5, v4, s[18:19] offset:256
	global_atomic_add v5, v4, s[18:19] offset:512
	global_atomic_add v5, v4, s[18:19] offset:768
	global_atomic_add v5, v4, s[18:19] offset:1024
	global_atomic_add v5, v4, s[18:19] offset:1280
	global_atomic_add v5, v4, s[18:19] offset:1536
	global_atomic_add v5, v4, s[18:19] offset:1792
	global_atomic_add v5, v4, s[18:19] offset:2048
	global_atomic_add v5, v4, s[18:19] offset:2304
	global_atomic_add v5, v4, s[18:19] offset:2560
	global_atomic_add v5, v4, s[18:19] offset:2816
	global_atomic_add v5, v4, s[18:19] offset:3072
	global_atomic_add v5, v4, s[18:19] offset:3328
	global_atomic_add v5, v4, s[18:19] offset:3584
	global_atomic_add v5, v4, s[18:19] offset:3840
	s_branch .Lxb2_out

.Lxb2_spin:
	global_load_dword v1, v5, s[8:9] sc1
	s_add_i32 s22, s22, 1
	s_waitcnt vmcnt(0)
	v_cmp_ne_u32_e32 vcc, 1, v1
	s_cbranch_vccnz .Lxb2_out
	s_sleep 1
	s_and_b32 s12, s22, 0xff
	s_cmp_lg_u32 s12, 0
	s_cbranch_scc1 .Lxb2_spin
	global_load_dword v1, v5, s[14:15] sc1
	s_waitcnt vmcnt(0)
	v_cmp_ne_u32_e32 vcc, 0, v1
	s_cbranch_vccnz .Lxb2_out
	s_cmp_lt_u32 s22, 0x40001
	s_cbranch_scc1 .Lxb2_spin
	global_atomic_add v5, v4, s[14:15]
	s_waitcnt vmcnt(0)
.Lxb2_out:
.LBB0_731:
	s_or_b64 exec, exec, s[0:1]
	v_readlane_b32 s4, v254, 0
	v_readlane_b32 s5, v254, 1
	s_waitcnt lgkmcnt(0)
	s_barrier
	v_mbcnt_lo_u32_b32 v0, -1, 0
	v_mbcnt_hi_u32_b32 v0, -1, v0
	v_readlane_b32 s0, v254, 3
	s_cmpk_lt_i32 s88, 0x55
	s_cselect_b64 s[14:15], -1, 0
	v_add_u32_e32 v0, s0, v0
	s_cmpk_gt_i32 s88, 0x54
	v_readfirstlane_b32 s6, v0
	s_cbranch_scc1 .LBB0_1114
	v_lshlrev_b32_e32 v1, 4, v0
	v_add_u32_e32 v2, 0x2000, v1
	v_ashrrev_i32_e32 v3, 31, v2
	v_lshrrev_b32_e32 v3, 22, v3
	v_add_u32_e32 v3, v2, v3
	s_load_dwordx4 s[16:19], s[4:5], 0x78
	s_load_dwordx4 s[0:3], s[4:5], 0x50
	v_ashrrev_i32_e32 v10, 10, v3
	v_mul_i32_i24_e32 v3, 0x400, v10
	v_sub_u32_e32 v2, v2, v3
	v_lshrrev_b32_e32 v3, 4, v2
	s_waitcnt lgkmcnt(0)
	s_add_u32 s55, s18, 0x1000000
	v_bitop3_b32 v2, v3, v2, 32 bitop3:0x6c
	s_addc_u32 s69, s19, 0
	v_ashrrev_i32_e32 v3, 31, v2
	s_add_u32 s71, s18, 0x200000
	v_lshrrev_b32_e32 v3, 26, v3
	s_addc_u32 s76, s19, 0
	s_ashr_i32 s5, s6, 6
	v_add_u32_e32 v3, v2, v3
	v_lshlrev_b32_e32 v4, 3, v10
	s_ashr_i32 s4, s6, 8
	s_sub_i32 s7, s88, 64
	s_lshl_b32 s77, s5, 10
	v_ashrrev_i32_e32 v11, 6, v3
	v_and_b32_e32 v4, -16, v4
	s_cmp_lt_i32 s88, 64
	v_add_u32_e32 v4, v11, v4
	s_cselect_b32 s20, s88, s7
	v_and_b32_e32 v5, 3, v11
	s_mov_b32 s7, 0x1fffe0
	v_lshrrev_b32_e32 v6, 2, v4
	v_lshlrev_b32_e32 v7, 1, v4
	v_and_b32_e32 v3, 0xc0, v3
	v_and_or_b32 v5, v4, s7, v5
	v_and_b32_e32 v6, 4, v6
	v_and_b32_e32 v7, 24, v7
	v_sub_u32_e32 v2, v2, v3
	v_mov_b32_e32 v3, 1
	v_or3_b32 v5, v5, v6, v7
	v_lshlrev_b32_e32 v6, 5, v10
	v_ashrrev_i16_sdwa v2, v3, sext(v2) dst_sel:DWORD dst_unused:UNUSED_PAD src0_sel:DWORD src1_sel:BYTE_0
	v_and_b32_e32 v6, 32, v6
	v_bfe_i32 v12, v2, 0, 16
	v_add_lshl_u32 v2, v6, v12, 1
	v_lshl_add_u32 v188, v5, 11, v2
	v_lshl_add_u32 v190, v4, 11, v2
	v_bfe_i32 v2, v0, 27, 1
	v_lshrrev_b32_e32 v2, 22, v2
	v_add_u32_e32 v2, v1, v2
	v_and_b32_e32 v2, 0xfffffc00, v2
	v_sub_u32_e32 v1, v1, v2
	v_lshrrev_b32_e32 v2, 4, v1
	v_ashrrev_i32_e32 v4, 31, v0
	v_bitop3_b32 v1, v2, v1, 32 bitop3:0x6c
	v_lshrrev_b32_e32 v4, 26, v4
	v_ashrrev_i32_e32 v2, 31, v1
	v_add_u32_e32 v4, v0, v4
	v_lshrrev_b32_e32 v2, 26, v2
	v_ashrrev_i32_e32 v14, 6, v4
	v_add_u32_e32 v2, v1, v2
	v_lshlrev_b32_e32 v4, 3, v14
	v_ashrrev_i32_e32 v13, 6, v2
	v_and_b32_e32 v4, -16, v4
	v_add_u32_e32 v4, v13, v4
	v_and_b32_e32 v5, 3, v13
	v_lshrrev_b32_e32 v6, 2, v4
	v_lshlrev_b32_e32 v7, 1, v4
	v_and_b32_e32 v2, 0xc0, v2
	s_cselect_b32 s78, 20, 19
	v_and_or_b32 v5, v4, s7, v5
	v_and_b32_e32 v6, 4, v6
	v_and_b32_e32 v7, 24, v7
	v_sub_u32_e32 v1, v1, v2
	s_ashr_i32 s21, s20, 31
	v_or3_b32 v5, v5, v6, v7
	v_lshlrev_b32_e32 v6, 5, v14
	v_ashrrev_i16_sdwa v1, v3, sext(v1) dst_sel:DWORD dst_unused:UNUSED_PAD src0_sel:DWORD src1_sel:BYTE_0
	s_lshl_b64 s[8:9], s[20:21], 19
	s_lshl_b32 s7, s78, 19
	v_and_b32_e32 v6, 32, v6
	v_bfe_i32 v15, v1, 0, 16
	s_add_u32 s26, s71, s7
	v_add_lshl_u32 v1, v6, v15, 1
	s_addc_u32 s27, s76, 0
	s_add_i32 s21, s77, 0
	v_lshl_add_u32 v192, v5, 11, v1
	s_add_i32 m0, s21, 0x10000
	v_lshl_add_u32 v194, v4, 11, v1
	global_load_lds_dwordx4 v192, s[26:27]
	s_add_i32 m0, s21, 0x12000
	s_add_u32 s10, s26, 0x40000
	global_load_lds_dwordx4 v188, s[26:27]
	s_addc_u32 s11, s27, 0
	s_add_i32 m0, s21, 0x14000
	v_mov_b32_e32 v1, 0
	global_load_lds_dwordx4 v192, s[10:11]
	s_add_i32 m0, s21, 0x16000
	s_add_u32 s28, s55, s8
	s_addc_u32 s29, s69, s9
	s_add_i32 s79, s21, 0x2000
	global_load_lds_dwordx4 v188, s[10:11]
	s_mov_b32 m0, s21
	s_add_u32 s8, s28, 0x40000
	global_load_lds_dwordx4 v194, s[28:29]
	s_mov_b32 m0, s79
	s_addc_u32 s9, s29, 0
	s_add_i32 s80, s21, 0x4000
	global_load_lds_dwordx4 v190, s[28:29]
	s_mov_b32 m0, s80
	s_add_i32 s81, s21, 0x6000
	global_load_lds_dwordx4 v194, s[8:9]
	s_mov_b32 m0, s81
	v_mov_b32_e32 v193, v1
	global_load_lds_dwordx4 v190, s[8:9]
	v_mov_b32_e32 v189, v1
	v_mov_b32_e32 v195, v1
	v_mov_b32_e32 v191, v1
	s_cmp_eq_u32 s4, 1
	s_mov_b32 s23, 0
	v_lshl_add_u64 v[8:9], s[26:27], 0, v[192:193]
	v_lshl_add_u64 v[6:7], s[26:27], 0, v[188:189]
	v_lshl_add_u64 v[4:5], s[28:29], 0, v[194:195]
	v_lshl_add_u64 v[2:3], s[28:29], 0, v[190:191]
	s_cselect_b64 s[24:25], -1, 0
	s_cmp_lg_u32 s4, 1
	s_movk_i32 s82, 0x4000
	s_cbranch_scc1 .LBB0_734
	s_barrier

.LBB0_2292:
	v_readlane_b32 s2, v254, 8
	v_readlane_b32 s6, v254, 6
	v_readlane_b32 s7, v254, 7
	v_readlane_b32 s4, v254, 4
	v_readlane_b32 s5, v254, 5
	s_lshl_b32 s2, s2, 8
	s_add_u32 s2, s6, s2
	s_addc_u32 s3, s7, 0
	s_add_u32 s8, s2, 0x2400
	s_addc_u32 s9, s3, 0
	s_add_u32 s2, s2, 0x1400
	s_addc_u32 s3, s3, 0
	s_add_u32 s14, s4, 0x4200
	s_addc_u32 s15, s5, 0
	s_add_u32 s16, s4, 0x7400
	s_addc_u32 s17, s5, 0
	s_add_u32 s18, s6, 0x2400
	s_addc_u32 s19, s7, 0
	v_mov_b32_e32 v4, 1
	v_mov_b32_e32 v5, 0
	global_atomic_add v3, v5, v4, s[2:3] sc0
	s_waitcnt vmcnt(0) lgkmcnt(0)
	buffer_inv sc1
	v_readfirstlane_b32 s10, v2
	v_readfirstlane_b32 s11, v0
	v_readfirstlane_b32 s12, v3
	s_mul_i32 s10, s10, 3
	s_mul_i32 s11, s11, 3
	s_add_i32 s12, s12, 1
	s_cmp_lg_u32 s12, s10
	s_cbranch_scc1 .Lxb3_poll
	buffer_wbl2 sc1
	s_waitcnt vmcnt(0)
	global_atomic_add v3, v5, v4, s[16:17] sc0
	s_waitcnt vmcnt(0)
	v_readfirstlane_b32 s12, v3
	s_add_i32 s12, s12, 1
	s_cmp_lg_u32 s12, s11
	s_cbranch_scc1 .Lxb3_poll
	global_atomic_add v5, v4, s[18:19]
	global_atomic_add v5, v4, s[18:19] offset:256
	global_atomic_add v5, v4, s[18:19] offset:512
	global_atomic_add v5, v4, s[18:19] offset:768
	global_atomic_add v5, v4, s[18:19] offset:1024
	global_atomic_add v5, v4, s[18:19] offset:1280
	global_atomic_add v5, v4, s[18:19] offset:1536
	global_atomic_add v5, v4, s[18:19] offset:1792
	global_atomic_add v5, v4, s[18:19] offset:2048
	global_atomic_add v5, v4, s[18:19] offset:2304
	global_atomic_add v5, v4, s[18:19] offset:2560
	global_atomic_add v5, v4, s[18:19] offset:2816
	global_atomic_add v5, v4, s[18:19] offset:3072
	global_atomic_add v5, v4, s[18:19] offset:3328
	global_atomic_add v5, v4, s[18:19] offset:3584
	global_atomic_add v5, v4, s[18:19] offset:3840
	s_branch .Lxb3_out

.Lxb3_spin:
	global_load_dword v1, v5, s[8:9] sc1
	s_add_i32 s22, s22, 1
	s_waitcnt vmcnt(0)
	v_cmp_ne_u32_e32 vcc, 2, v1
	s_cbranch_vccnz .Lxb3_out
	s_sleep 1
	s_and_b32 s12, s22, 0xff
	s_cmp_lg_u32 s12, 0
	s_cbranch_scc1 .Lxb3_spin
	global_load_dword v1, v5, s[14:15] sc1
	s_waitcnt vmcnt(0)
	v_cmp_ne_u32_e32 vcc, 0, v1
	s_cbranch_vccnz .Lxb3_out
	s_cmp_lt_u32 s22, 0x40001
	s_cbranch_scc1 .Lxb3_spin
	global_atomic_add v5, v4, s[14:15]
	s_waitcnt vmcnt(0)
.Lxb3_out:
.LBB0_2328:
	s_or_b64 exec, exec, s[0:1]
	s_and_b32 s57, s96, 24
	s_cmp_lg_u32 s57, 0
	s_waitcnt lgkmcnt(0)
	s_barrier
	s_cbranch_scc1 .LBB0_2478
	v_readlane_b32 s0, v254, 0
	v_readlane_b32 s1, v254, 1
	s_and_b64 vcc, exec, s[52:53]
	v_mbcnt_lo_u32_b32 v0, -1, 0
	v_mbcnt_hi_u32_b32 v0, -1, v0
	s_cbranch_vccnz .LBB0_2478
	s_load_dwordx4 s[20:23], s[0:1], 0x78
	v_and_b32_e32 v1, 63, v0
	v_lshlrev_b32_e32 v6, 5, v1
	v_mov_b32_e32 v138, 0
	v_and_b32_e32 v2, 0x780, v6
	v_mov_b32_e32 v3, v138
	v_lshlrev_b32_e32 v4, 5, v0
	s_waitcnt lgkmcnt(0)
	v_lshl_add_u64 v[2:3], s[22:23], 0, v[2:3]
	v_and_b32_e32 v4, 0x60, v4
	v_mov_b32_e32 v5, v138
	s_load_dwordx4 s[24:27], s[0:1], 0x10
	s_load_dwordx2 s[28:29], s[0:1], 0x30
	v_lshl_add_u64 v[2:3], v[2:3], 0, v[4:5]
	s_mov_b64 s[0:1], 0xc900000
	v_lshl_add_u64 v[140:141], v[2:3], 0, s[0:1]
	v_lshl_add_u64 v[2:3], s[22:23], 0, v[4:5]
	s_mov_b64 s[0:1], 0xea00000
	v_lshl_add_u64 v[142:143], v[2:3], 0, s[0:1]
	v_mbcnt_lo_u32_b32 v2, -1, 0
	v_mbcnt_hi_u32_b32 v7, -1, v2
	v_and_b32_e32 v8, 64, v7
	v_xor_b32_e32 v2, 1, v7
	v_add_u32_e32 v9, 64, v8
	v_cmp_lt_i32_e32 vcc, v2, v9
	v_mov_b32_e32 v3, v138
	v_readlane_b32 s2, v254, 3
	v_cndmask_b32_e32 v2, v7, v2, vcc
	v_lshlrev_b32_e32 v182, 2, v2
	v_xor_b32_e32 v2, 2, v7
	v_cmp_lt_i32_e32 vcc, v2, v9
	v_add_u32_e32 v136, s2, v0
	s_mov_b64 s[0:1], 0xed00000
	v_cndmask_b32_e32 v2, v7, v2, vcc
	v_lshlrev_b32_e32 v183, 2, v2
	v_and_b32_e32 v2, 60, v0
	v_lshl_add_u64 v[4:5], s[22:23], 0, v[2:3]
	v_xor_b32_e32 v3, 4, v7
	v_cmp_lt_i32_e32 vcc, v3, v9
	v_ashrrev_i32_e32 v137, 31, v136
	v_lshl_add_u64 v[144:145], v[4:5], 0, s[0:1]
	v_cndmask_b32_e32 v3, v7, v3, vcc
	v_lshlrev_b32_e32 v184, 2, v3
	v_xor_b32_e32 v3, 8, v7
	v_cmp_lt_i32_e32 vcc, v3, v9
	v_lshl_add_u64 v[4:5], v[136:137], 2, s[22:23]
	s_mov_b64 s[2:3], 0x12500000
	v_cndmask_b32_e32 v3, v7, v3, vcc
	v_lshlrev_b32_e32 v185, 2, v3
	v_xor_b32_e32 v3, 16, v7
	v_cmp_lt_i32_e32 vcc, v3, v9
	v_lshl_add_u64 v[146:147], v[4:5], 0, s[2:3]
	v_add_u32_e32 v4, -1, v7
	v_cndmask_b32_e32 v3, v7, v3, vcc
	v_lshlrev_b32_e32 v186, 2, v3
	v_xor_b32_e32 v3, 32, v7
	v_cmp_lt_i32_e32 vcc, v3, v9
	s_add_u32 s34, s20, 0x8700000
	s_addc_u32 s35, s21, 0
	v_cndmask_b32_e32 v3, v7, v3, vcc
	v_cmp_lt_i32_e32 vcc, v4, v8
	v_mov_b32_e32 v5, v138
	v_lshlrev_b32_e32 v187, 2, v3
	v_cndmask_b32_e32 v4, v4, v7, vcc
	v_lshlrev_b32_e32 v189, 2, v4
	v_add_u32_e32 v4, -2, v7
	v_cmp_lt_i32_e32 vcc, v4, v8
	v_lshlrev_b32_e32 v3, 2, v136
	s_add_u32 s36, s20, 0x8780000
	v_cndmask_b32_e32 v4, v4, v7, vcc
	v_lshlrev_b32_e32 v190, 2, v4
	v_add_u32_e32 v4, -4, v7
	v_cmp_lt_i32_e32 vcc, v4, v8
	s_mov_b64 s[18:19], 0x6400000
	v_and_b32_e32 v0, 7, v0
	v_cndmask_b32_e32 v4, v4, v7, vcc
	v_lshlrev_b32_e32 v191, 2, v4
	v_add_u32_e32 v4, -8, v7
	v_cmp_lt_i32_e32 vcc, v4, v8
	v_ashrrev_i32_e32 v149, 6, v136
	v_cmp_eq_u32_e64 s[0:1], 0, v1
	v_cndmask_b32_e32 v4, v4, v7, vcc
	v_lshlrev_b32_e32 v192, 2, v4
	v_add_u32_e32 v4, -16, v7
	v_cmp_lt_i32_e32 vcc, v4, v8
	v_add_u32_e32 v188, 0, v3
	v_cmp_gt_u32_e64 s[4:5], 2, v1
	v_cndmask_b32_e32 v4, v4, v7, vcc
	v_lshlrev_b32_e32 v193, 2, v4
	v_subrev_u32_e32 v4, 32, v7
	v_cmp_lt_i32_e32 vcc, v4, v8
	v_cmp_gt_u32_e64 s[6:7], 4, v1
	v_cmp_gt_u32_e64 s[8:9], 8, v1
	v_cndmask_b32_e32 v4, v4, v7, vcc
	v_lshlrev_b32_e32 v194, 2, v4
	v_lshlrev_b32_e32 v4, 4, v1
	v_lshl_add_u64 v[4:5], s[22:23], 0, v[4:5]
	v_cmp_gt_u32_e64 s[10:11], 16, v1
	v_cmp_gt_u32_e64 s[12:13], 32, v1
	v_cmp_eq_u32_e64 s[14:15], 63, v1
	s_addc_u32 s37, s21, 0
	v_lshlrev_b32_e32 v148, 3, v1
	v_lshl_add_u64 v[150:151], v[4:5], 0, s[18:19]
	v_cmp_eq_u32_e64 s[18:19], 0, v0
	v_lshl_add_u64 v[0:1], v[136:137], 1, s[22:23]
	s_mov_b64 s[20:21], 0x9700000
	s_movk_i32 s33, 0x100
	v_add_u32_e32 v211, v188, v3
	v_add_u32_e32 v212, 0, v2
	v_lshlrev_b32_e32 v2, 3, v149
	v_sub_u32_e32 v3, 0, v3
	v_lshl_add_u64 v[152:153], v[0:1], 0, s[20:21]
	s_mov_b64 s[20:21], 0x10400400
	s_mov_b32 s31, 0
	v_cmp_gt_i32_e64 s[2:3], 8, v136
	v_cmp_gt_i32_e64 s[16:17], s33, v136
	v_add_u32_e32 v195, 0x200, v136
	v_add_u32_e32 v196, 0x400, v136
	v_add_u32_e32 v197, 0x600, v136
	v_add_u32_e32 v198, 0x800, v136
	v_add_u32_e32 v199, 0xa00, v136
	v_add_u32_e32 v200, 0xc00, v136
	v_add_u32_e32 v201, 0xe00, v136
	v_add_u32_e32 v202, 0x1000, v136
	v_add_u32_e32 v203, 0x1200, v136
	v_add_u32_e32 v204, 0x1400, v136
	v_add_u32_e32 v205, 0x1600, v136
	v_add_u32_e32 v206, 0x1800, v136
	v_add_u32_e32 v207, 0x1a00, v136
	v_add_u32_e32 v208, 0x1c00, v136
	v_add_u32_e32 v209, 0x1e00, v136
	v_add_u32_e32 v210, 0x2000, v136
	v_add_u32_e32 v213, 0, v6
	v_lshl_add_u64 v[154:155], v[0:1], 0, s[20:21]
	s_mov_b32 s44, 0xff800000
	s_mov_b32 s45, 0xff61b1e6
	s_mov_b32 s46, 0xf800000
	v_mov_b32_e32 v137, 0x260
	s_mov_b32 s47, 0x43800000
	s_mov_b32 s48, 0x800000
	s_mov_b32 s49, 0x3f317217
	s_mov_b32 s50, 0x7f800000
	v_mov_b32_e32 v214, -1
	s_movk_i32 s51, 0x1fff
	s_mov_b32 s52, 0x3f800
	v_add_u32_e32 v215, 0, v2
	v_add_u32_e32 v216, v211, v3
	s_movk_i32 s53, 0x7fff
	v_mov_b32_e32 v217, 0xff800000
	v_mov_b32_e32 v218, 0x41b17218
	v_mov_b32_e32 v219, 0xff61b1e6
	s_mov_b32 s54, s96
	s_branch .LBB0_2332

.LBB0_3527:
	v_readlane_b32 s2, v254, 8
	v_readlane_b32 s6, v254, 6
	v_readlane_b32 s7, v254, 7
	v_readlane_b32 s4, v254, 4
	v_readlane_b32 s5, v254, 5
	s_lshl_b32 s2, s2, 8
	s_add_u32 s2, s6, s2
	s_addc_u32 s3, s7, 0
	s_add_u32 s8, s2, 0x2400
	s_addc_u32 s9, s3, 0
	s_add_u32 s2, s2, 0x1400
	s_addc_u32 s3, s3, 0
	s_add_u32 s14, s4, 0x4200
	s_addc_u32 s15, s5, 0
	s_add_u32 s16, s4, 0x7400
	s_addc_u32 s17, s5, 0
	s_add_u32 s18, s6, 0x2400
	s_addc_u32 s19, s7, 0
	v_mov_b32_e32 v4, 1
	v_mov_b32_e32 v5, 0
	global_atomic_add v3, v5, v4, s[2:3] sc0
	s_waitcnt vmcnt(0) lgkmcnt(0)
	buffer_inv sc1
	v_readfirstlane_b32 s10, v2
	v_readfirstlane_b32 s11, v0
	v_readfirstlane_b32 s12, v3
	s_mul_i32 s10, s10, 4
	s_mul_i32 s11, s11, 4
	s_add_i32 s12, s12, 1
	s_cmp_lg_u32 s12, s10
	s_cbranch_scc1 .Lxb4_poll
	buffer_wbl2 sc1
	s_waitcnt vmcnt(0)
	global_atomic_add v3, v5, v4, s[16:17] sc0
	s_waitcnt vmcnt(0)
	v_readfirstlane_b32 s12, v3
	s_add_i32 s12, s12, 1
	s_cmp_lg_u32 s12, s11
	s_cbranch_scc1 .Lxb4_poll
	global_atomic_add v5, v4, s[18:19]
	global_atomic_add v5, v4, s[18:19] offset:256
	global_atomic_add v5, v4, s[18:19] offset:512
	global_atomic_add v5, v4, s[18:19] offset:768
	global_atomic_add v5, v4, s[18:19] offset:1024
	global_atomic_add v5, v4, s[18:19] offset:1280
	global_atomic_add v5, v4, s[18:19] offset:1536
	global_atomic_add v5, v4, s[18:19] offset:1792
	global_atomic_add v5, v4, s[18:19] offset:2048
	global_atomic_add v5, v4, s[18:19] offset:2304
	global_atomic_add v5, v4, s[18:19] offset:2560
	global_atomic_add v5, v4, s[18:19] offset:2816
	global_atomic_add v5, v4, s[18:19] offset:3072
	global_atomic_add v5, v4, s[18:19] offset:3328
	global_atomic_add v5, v4, s[18:19] offset:3584
	global_atomic_add v5, v4, s[18:19] offset:3840
	s_branch .Lxb4_out

.Lxb4_spin:
	global_load_dword v1, v5, s[8:9] sc1
	s_add_i32 s22, s22, 1
	s_waitcnt vmcnt(0)
	v_cmp_ne_u32_e32 vcc, 3, v1
	s_cbranch_vccnz .Lxb4_out
	s_sleep 1
	s_and_b32 s12, s22, 0xff
	s_cmp_lg_u32 s12, 0
	s_cbranch_scc1 .Lxb4_spin
	global_load_dword v1, v5, s[14:15] sc1
	s_waitcnt vmcnt(0)
	v_cmp_ne_u32_e32 vcc, 0, v1
	s_cbranch_vccnz .Lxb4_out
	s_cmp_lt_u32 s22, 0x40001
	s_cbranch_scc1 .Lxb4_spin
	global_atomic_add v5, v4, s[14:15]
	s_waitcnt vmcnt(0)
.Lxb4_out:
.LBB0_3563:
	s_or_b64 exec, exec, s[0:1]
	v_readlane_b32 s0, v254, 0
	v_readlane_b32 s1, v254, 1
	s_waitcnt lgkmcnt(0)
	s_barrier
	s_load_dwordx2 s[2:3], s[0:1], 0x80
	v_readlane_b32 s0, v254, 3
	v_mbcnt_lo_u32_b32 v0, -1, 0
	v_mbcnt_hi_u32_b32 v0, -1, v0
	s_and_b64 vcc, exec, s[52:53]
	s_mov_b32 s10, 0
	v_add_u32_e32 v4, s0, v0
	s_cbranch_vccnz .LBB0_3568
	v_and_b32_e32 v1, 63, v0
	v_and_b32_e32 v6, 15, v0
	v_bfe_u32 v0, v0, 4, 2
	v_lshl_add_u32 v8, v1, 4, 0
	v_and_b32_e32 v1, 0xfffffc0, v4
	v_lshlrev_b32_e32 v7, 3, v0
	v_lshl_add_u32 v10, v1, 4, v8
	v_ashrrev_i32_e32 v1, 3, v4
	v_lshlrev_b32_e32 v0, 2, v0
	s_waitcnt lgkmcnt(0)
	s_add_u32 s4, s2, 0x12400000
	v_and_or_b32 v11, v1, -16, v0
	v_and_b32_e32 v0, 64, v4
	v_mov_b32_e32 v1, 0
	s_addc_u32 s5, s3, 0
	s_movk_i32 s0, 0x100
	v_lshl_add_u64 v[2:3], s[2:3], 0, v[0:1]
	v_lshlrev_b32_e32 v0, 2, v6
	s_add_u32 s6, s2, 0xd00000
	v_cmp_gt_i32_e32 vcc, s0, v4
	v_lshl_add_u64 v[2:3], v[2:3], 0, v[0:1]
	s_mov_b64 s[0:1], 0x12e00000
	v_ashrrev_i32_e32 v5, 6, v4
	s_addc_u32 s7, s3, 0
	s_mov_b32 s9, 0
	v_lshl_add_u32 v9, v4, 4, 0
	v_lshl_add_u64 v[2:3], v[2:3], 0, s[0:1]
	s_lshl_b32 s11, s96, 5
	s_lshl_b32 s12, s56, 5
	s_mov_b32 s13, 0x8000
	s_mov_b32 s14, s96
	s_branch .LBB0_3566
